# GEMM tile headers zero the 128 accumulators with 64 v_mov_b64 instead of 128 v_mov_b32; on top of flat barrier release
# speedup vs baseline: 1.0049x; 1.0017x over previous
.LBB0_264:
	s_ashr_i32 s55, s54, 31
	s_lshl_b64 s[56:57], s[54:55], 20
	s_add_u32 s56, s10, s56
	s_addc_u32 s57, s11, s57
	s_and_b64 s[58:59], s[4:5], exec
	s_cselect_b32 s55, s57, s63
	s_cselect_b32 s61, s56, s62
	s_ashr_i32 s51, s50, 31
	s_lshl_b64 s[58:59], s[50:51], 20
	s_add_u32 s58, s46, s58
	s_addc_u32 s59, s47, s59
	s_and_b64 s[66:67], s[4:5], exec
	s_cselect_b32 s51, s59, s65
	s_cselect_b32 s68, s58, s64
	s_add_u32 s62, s62, 0x80080
	s_addc_u32 s63, s63, 0
	s_add_u32 s69, s64, 0x100
	s_addc_u32 s94, s65, 0
	s_mov_b32 s95, -2
	s_waitcnt vmcnt(0)
	v_mov_b64_e32 v[0:1], 0
	v_mov_b64_e32 v[2:3], 0
	v_mov_b64_e32 v[4:5], 0
	v_mov_b64_e32 v[6:7], 0
	v_mov_b64_e32 v[8:9], 0
	v_mov_b64_e32 v[10:11], 0
	v_mov_b64_e32 v[12:13], 0
	v_mov_b64_e32 v[14:15], 0
	v_mov_b64_e32 v[16:17], 0
	v_mov_b64_e32 v[18:19], 0
	v_mov_b64_e32 v[20:21], 0
	v_mov_b64_e32 v[22:23], 0
	v_mov_b64_e32 v[24:25], 0
	v_mov_b64_e32 v[26:27], 0
	v_mov_b64_e32 v[28:29], 0
	v_mov_b64_e32 v[30:31], 0
	v_mov_b64_e32 v[32:33], 0
	v_mov_b64_e32 v[34:35], 0
	v_mov_b64_e32 v[36:37], 0
	v_mov_b64_e32 v[38:39], 0
	v_mov_b64_e32 v[40:41], 0
	v_mov_b64_e32 v[42:43], 0
	v_mov_b64_e32 v[44:45], 0
	v_mov_b64_e32 v[46:47], 0
	v_mov_b64_e32 v[48:49], 0
	v_mov_b64_e32 v[50:51], 0
	v_mov_b64_e32 v[52:53], 0
	v_mov_b64_e32 v[54:55], 0
	v_mov_b64_e32 v[56:57], 0
	v_mov_b64_e32 v[58:59], 0
	v_mov_b64_e32 v[60:61], 0
	v_mov_b64_e32 v[62:63], 0
	v_mov_b64_e32 v[64:65], 0
	v_mov_b64_e32 v[66:67], 0
	v_mov_b64_e32 v[68:69], 0
	v_mov_b64_e32 v[70:71], 0
	v_mov_b64_e32 v[72:73], 0
	v_mov_b64_e32 v[74:75], 0
	v_mov_b64_e32 v[76:77], 0
	v_mov_b64_e32 v[78:79], 0
	v_mov_b64_e32 v[80:81], 0
	v_mov_b64_e32 v[82:83], 0
	v_mov_b64_e32 v[84:85], 0
	v_mov_b64_e32 v[86:87], 0
	v_mov_b64_e32 v[88:89], 0
	v_mov_b64_e32 v[90:91], 0
	v_mov_b64_e32 v[92:93], 0
	v_mov_b64_e32 v[94:95], 0
	v_mov_b64_e32 v[96:97], 0
	v_mov_b64_e32 v[98:99], 0
	v_mov_b64_e32 v[100:101], 0
	v_mov_b64_e32 v[102:103], 0
	v_mov_b64_e32 v[104:105], 0
	v_mov_b64_e32 v[106:107], 0
	v_mov_b64_e32 v[108:109], 0
	v_mov_b64_e32 v[110:111], 0
	v_mov_b64_e32 v[112:113], 0
	v_mov_b64_e32 v[114:115], 0
	v_mov_b64_e32 v[116:117], 0
	v_mov_b64_e32 v[118:119], 0
	v_mov_b64_e32 v[120:121], 0
	v_mov_b64_e32 v[122:123], 0
	v_mov_b64_e32 v[124:125], 0
	v_mov_b64_e32 v[126:127], 0
	s_nop 0
	s_nop 0
	s_nop 0
	s_nop 0
	s_nop 0
	s_nop 0
	s_nop 0
	s_nop 0
	s_nop 0
	s_nop 0
	s_nop 0
	s_nop 0
	s_nop 0
	s_nop 0
	s_nop 0

.LBB0_488:
	s_ashr_i32 s45, s44, 31
	s_lshl_b64 s[46:47], s[44:45], 20
	s_add_u32 s46, s61, s46
	s_addc_u32 s47, s62, s47
	s_and_b64 s[48:49], s[4:5], exec
	s_cselect_b32 s45, s47, s55
	s_cselect_b32 s51, s46, s54
	s_ashr_i32 s43, s42, 31
	s_lshl_b64 s[48:49], s[42:43], 20
	s_add_u32 s48, s10, s48
	s_addc_u32 s49, s11, s49
	s_and_b64 s[58:59], s[4:5], exec
	s_cselect_b32 s43, s49, s57
	s_cselect_b32 s83, s48, s56
	s_add_u32 s54, s54, 0x80080
	s_addc_u32 s55, s55, 0
	s_add_u32 s84, s56, 0x100
	s_addc_u32 s85, s57, 0
	s_mov_b32 s86, -2
	v_mov_b64_e32 v[0:1], 0
	v_mov_b64_e32 v[2:3], 0
	v_mov_b64_e32 v[4:5], 0
	v_mov_b64_e32 v[6:7], 0
	v_mov_b64_e32 v[8:9], 0
	v_mov_b64_e32 v[10:11], 0
	v_mov_b64_e32 v[12:13], 0
	v_mov_b64_e32 v[14:15], 0
	v_mov_b64_e32 v[16:17], 0
	v_mov_b64_e32 v[18:19], 0
	v_mov_b64_e32 v[20:21], 0
	v_mov_b64_e32 v[22:23], 0
	v_mov_b64_e32 v[24:25], 0
	v_mov_b64_e32 v[26:27], 0
	v_mov_b64_e32 v[28:29], 0
	v_mov_b64_e32 v[30:31], 0
	v_mov_b64_e32 v[32:33], 0
	v_mov_b64_e32 v[34:35], 0
	v_mov_b64_e32 v[36:37], 0
	v_mov_b64_e32 v[38:39], 0
	v_mov_b64_e32 v[40:41], 0
	v_mov_b64_e32 v[42:43], 0
	v_mov_b64_e32 v[44:45], 0
	v_mov_b64_e32 v[46:47], 0
	v_mov_b64_e32 v[48:49], 0
	v_mov_b64_e32 v[50:51], 0
	v_mov_b64_e32 v[52:53], 0
	v_mov_b64_e32 v[54:55], 0
	v_mov_b64_e32 v[56:57], 0
	v_mov_b64_e32 v[58:59], 0
	v_mov_b64_e32 v[60:61], 0
	v_mov_b64_e32 v[62:63], 0
	v_mov_b64_e32 v[64:65], 0
	v_mov_b64_e32 v[66:67], 0
	v_mov_b64_e32 v[68:69], 0
	v_mov_b64_e32 v[70:71], 0
	v_mov_b64_e32 v[72:73], 0
	v_mov_b64_e32 v[74:75], 0
	v_mov_b64_e32 v[76:77], 0
	v_mov_b64_e32 v[78:79], 0
	v_mov_b64_e32 v[80:81], 0
	v_mov_b64_e32 v[82:83], 0
	v_mov_b64_e32 v[84:85], 0
	v_mov_b64_e32 v[86:87], 0
	v_mov_b64_e32 v[88:89], 0
	v_mov_b64_e32 v[90:91], 0
	v_mov_b64_e32 v[92:93], 0
	v_mov_b64_e32 v[94:95], 0
	v_mov_b64_e32 v[96:97], 0
	v_mov_b64_e32 v[98:99], 0
	v_mov_b64_e32 v[100:101], 0
	v_mov_b64_e32 v[102:103], 0
	v_mov_b64_e32 v[104:105], 0
	v_mov_b64_e32 v[106:107], 0
	v_mov_b64_e32 v[108:109], 0
	v_mov_b64_e32 v[110:111], 0
	v_mov_b64_e32 v[112:113], 0
	v_mov_b64_e32 v[114:115], 0
	v_mov_b64_e32 v[116:117], 0
	v_mov_b64_e32 v[118:119], 0
	v_mov_b64_e32 v[120:121], 0
	v_mov_b64_e32 v[122:123], 0
	v_mov_b64_e32 v[124:125], 0
	v_mov_b64_e32 v[126:127], 0
	s_nop 0
	s_nop 0
	s_nop 0
	s_nop 0
	s_nop 0
	s_nop 0
	s_nop 0

.LBB0_671:
	s_ashr_i32 s51, s50, 31
	s_lshl_b64 s[52:53], s[50:51], 20
	s_add_u32 s52, s10, s52
	s_addc_u32 s53, s11, s53
	s_and_b64 s[54:55], s[6:7], exec
	s_cselect_b32 s51, s53, s61
	s_cselect_b32 s57, s52, s60
	s_ashr_i32 s49, s48, 31
	s_lshl_b64 s[54:55], s[48:49], 20
	s_add_u32 s54, s34, s54
	s_addc_u32 s55, s35, s55
	s_and_b64 s[64:65], s[6:7], exec
	s_cselect_b32 s49, s55, s63
	s_cselect_b32 s77, s54, s62
	s_add_u32 s60, s60, 0x80080
	s_addc_u32 s61, s61, 0
	s_add_u32 s81, s62, 0x100
	s_addc_u32 s82, s63, 0
	s_mov_b32 s83, -2
	s_waitcnt lgkmcnt(0)
	v_mov_b64_e32 v[0:1], 0
	v_mov_b64_e32 v[2:3], 0
	v_mov_b64_e32 v[4:5], 0
	v_mov_b64_e32 v[6:7], 0
	v_mov_b64_e32 v[8:9], 0
	v_mov_b64_e32 v[10:11], 0
	v_mov_b64_e32 v[12:13], 0
	v_mov_b64_e32 v[14:15], 0
	v_mov_b64_e32 v[16:17], 0
	v_mov_b64_e32 v[18:19], 0
	v_mov_b64_e32 v[20:21], 0
	v_mov_b64_e32 v[22:23], 0
	v_mov_b64_e32 v[24:25], 0
	v_mov_b64_e32 v[26:27], 0
	v_mov_b64_e32 v[28:29], 0
	v_mov_b64_e32 v[30:31], 0
	v_mov_b64_e32 v[32:33], 0
	v_mov_b64_e32 v[34:35], 0
	v_mov_b64_e32 v[36:37], 0
	v_mov_b64_e32 v[38:39], 0
	v_mov_b64_e32 v[40:41], 0
	v_mov_b64_e32 v[42:43], 0
	v_mov_b64_e32 v[44:45], 0
	v_mov_b64_e32 v[46:47], 0
	v_mov_b64_e32 v[48:49], 0
	v_mov_b64_e32 v[50:51], 0
	v_mov_b64_e32 v[52:53], 0
	v_mov_b64_e32 v[54:55], 0
	v_mov_b64_e32 v[56:57], 0
	v_mov_b64_e32 v[58:59], 0
	v_mov_b64_e32 v[60:61], 0
	v_mov_b64_e32 v[62:63], 0
	v_mov_b64_e32 v[64:65], 0
	v_mov_b64_e32 v[66:67], 0
	v_mov_b64_e32 v[68:69], 0
	v_mov_b64_e32 v[70:71], 0
	v_mov_b64_e32 v[72:73], 0
	v_mov_b64_e32 v[74:75], 0
	v_mov_b64_e32 v[76:77], 0
	v_mov_b64_e32 v[78:79], 0
	v_mov_b64_e32 v[80:81], 0
	v_mov_b64_e32 v[82:83], 0
	v_mov_b64_e32 v[84:85], 0
	v_mov_b64_e32 v[86:87], 0
	v_mov_b64_e32 v[88:89], 0
	v_mov_b64_e32 v[90:91], 0
	v_mov_b64_e32 v[92:93], 0
	v_mov_b64_e32 v[94:95], 0
	v_mov_b64_e32 v[96:97], 0
	v_mov_b64_e32 v[98:99], 0
	v_mov_b64_e32 v[100:101], 0
	v_mov_b64_e32 v[102:103], 0
	v_mov_b64_e32 v[104:105], 0
	v_mov_b64_e32 v[106:107], 0
	v_mov_b64_e32 v[108:109], 0
	v_mov_b64_e32 v[110:111], 0
	v_mov_b64_e32 v[112:113], 0
	v_mov_b64_e32 v[114:115], 0
	v_mov_b64_e32 v[116:117], 0
	v_mov_b64_e32 v[118:119], 0
	v_mov_b64_e32 v[120:121], 0
	v_mov_b64_e32 v[122:123], 0
	v_mov_b64_e32 v[124:125], 0
	v_mov_b64_e32 v[126:127], 0
	s_nop 0
	s_nop 0
	s_nop 0
	s_nop 0
	s_nop 0
	s_nop 0
	s_nop 0
	s_nop 0
	s_nop 0
	s_nop 0
	s_nop 0
	s_nop 0
	s_nop 0
	s_nop 0

.LBB0_787:
	s_ashr_i32 s39, s38, 31
	s_lshl_b64 s[40:41], s[38:39], 20
	s_add_u32 s40, s12, s40
	s_addc_u32 s41, s13, s41
	s_and_b64 s[42:43], s[4:5], exec
	s_cselect_b32 s39, s41, s49
	s_cselect_b32 s45, s40, s48
	s_ashr_i32 s37, s36, 31
	s_lshl_b64 s[42:43], s[36:37], 20
	s_add_u32 s42, s28, s42
	s_addc_u32 s43, s29, s43
	s_and_b64 s[52:53], s[4:5], exec
	s_cselect_b32 s37, s43, s51
	s_cselect_b32 s66, s42, s50
	s_add_u32 s48, s48, 0x80080
	s_addc_u32 s49, s49, 0
	s_add_u32 s67, s50, 0x100
	s_addc_u32 s68, s51, 0
	s_mov_b32 s69, -2
	s_waitcnt lgkmcnt(0)
	v_mov_b64_e32 v[0:1], 0
	v_mov_b64_e32 v[2:3], 0
	v_mov_b64_e32 v[4:5], 0
	v_mov_b64_e32 v[6:7], 0
	v_mov_b64_e32 v[8:9], 0
	v_mov_b64_e32 v[10:11], 0
	v_mov_b64_e32 v[12:13], 0
	v_mov_b64_e32 v[14:15], 0
	v_mov_b64_e32 v[16:17], 0
	v_mov_b64_e32 v[18:19], 0
	v_mov_b64_e32 v[20:21], 0
	v_mov_b64_e32 v[22:23], 0
	v_mov_b64_e32 v[24:25], 0
	v_mov_b64_e32 v[26:27], 0
	v_mov_b64_e32 v[28:29], 0
	v_mov_b64_e32 v[30:31], 0
	v_mov_b64_e32 v[32:33], 0
	v_mov_b64_e32 v[34:35], 0
	v_mov_b64_e32 v[36:37], 0
	v_mov_b64_e32 v[38:39], 0
	v_mov_b64_e32 v[40:41], 0
	v_mov_b64_e32 v[42:43], 0
	v_mov_b64_e32 v[44:45], 0
	v_mov_b64_e32 v[46:47], 0
	v_mov_b64_e32 v[48:49], 0
	v_mov_b64_e32 v[50:51], 0
	v_mov_b64_e32 v[52:53], 0
	v_mov_b64_e32 v[54:55], 0
	v_mov_b64_e32 v[56:57], 0
	v_mov_b64_e32 v[58:59], 0
	v_mov_b64_e32 v[60:61], 0
	v_mov_b64_e32 v[62:63], 0
	v_mov_b64_e32 v[64:65], 0
	v_mov_b64_e32 v[66:67], 0
	v_mov_b64_e32 v[68:69], 0
	v_mov_b64_e32 v[70:71], 0
	v_mov_b64_e32 v[72:73], 0
	v_mov_b64_e32 v[74:75], 0
	v_mov_b64_e32 v[76:77], 0
	v_mov_b64_e32 v[78:79], 0
	v_mov_b64_e32 v[80:81], 0
	v_mov_b64_e32 v[82:83], 0
	v_mov_b64_e32 v[84:85], 0
	v_mov_b64_e32 v[86:87], 0
	v_mov_b64_e32 v[88:89], 0
	v_mov_b64_e32 v[90:91], 0
	v_mov_b64_e32 v[92:93], 0
	v_mov_b64_e32 v[94:95], 0
	v_mov_b64_e32 v[96:97], 0
	v_mov_b64_e32 v[98:99], 0
	v_mov_b64_e32 v[100:101], 0
	v_mov_b64_e32 v[102:103], 0
	v_mov_b64_e32 v[104:105], 0
	v_mov_b64_e32 v[106:107], 0
	v_mov_b64_e32 v[108:109], 0
	v_mov_b64_e32 v[110:111], 0
	v_mov_b64_e32 v[112:113], 0
	v_mov_b64_e32 v[114:115], 0
	v_mov_b64_e32 v[116:117], 0
	v_mov_b64_e32 v[118:119], 0
	v_mov_b64_e32 v[120:121], 0
	v_mov_b64_e32 v[122:123], 0
	v_mov_b64_e32 v[124:125], 0
	v_mov_b64_e32 v[126:127], 0
	s_nop 0
	s_nop 0
	s_nop 0
	s_nop 0
	s_nop 0
	s_nop 0
	s_nop 0
	s_nop 0
	s_nop 0
	s_nop 0
	s_nop 0
	s_nop 0
